# plus A2: next-tile global loads moved into the MFMA-result wait slot after QK1; D: in-place init-tuple update skipped when unchanged
# baseline (speedup 1.0000x reference)
; __device__ __forceinline__ void softmax_tile(f32x16& p0, f32x16& p1, float& m, float& l, float& alpha, float cb, bf16x8& pa0, bf16x8& pa1, bf16x8& pa2, bf16x8& pa3) {
;   float mx_[4] = {p0[0], p0[1], p0[2], p0[3]};
; #pragma unroll
;   for (int r = 4; r < 16; ++r) mx_[r & 3] = fmaxf(mx_[r & 3], p0[r]);
; #pragma unroll
;   for (int r = 0; r < 16; ++r) mx_[r & 3] = fmaxf(mx_[r & 3], p1[r]);
;   float pmax = fmaxf(fmaxf(mx_[0], mx_[1]), fmaxf(mx_[2], mx_[3]));
;   { auto rr = __builtin_amdgcn_permlane32_swap(__float_as_uint(pmax), __float_as_uint(pmax), false, false);
;     pmax = fmaxf(__uint_as_float(rr[0]), __uint_as_float(rr[1])); }
;   pmax += cb;
;   float mn;
;   if (__builtin_expect(__all(pmax - m <= THR2), 1)) { mn = m; alpha = 1.f; }
;   else { mn = fmaxf(m, pmax); alpha = __builtin_amdgcn_exp2f(m - mn); m = mn; }
.Lmy_A_sm1x:
	v_max_f32_e32 v2, v160, v164
	v_max_f32_e32 v3, v161, v165
	v_max_f32_e32 v4, v163, v167
	v_max3_f32 v5, v162, v166, v170
	v_max3_f32 v4, v4, v171, v175
	v_max3_f32 v2, v2, v168, v172
	v_max3_f32 v3, v3, v169, v173
	v_max3_f32 v5, v5, v174, v146
	v_max3_f32 v4, v4, v147, v151
	v_max3_f32 v2, v2, v144, v148
	v_max3_f32 v3, v3, v145, v149
	v_max3_f32 v5, v5, v150, v154
	v_max3_f32 v4, v4, v155, v159
	v_max3_f32 v2, v2, v152, v156
	v_max3_f32 v3, v3, v153, v157
	v_max3_f32 v4, v5, v158, v4
	v_max3_f32 v2, v2, v3, v4
	v_cmp_ge_f32_e32 vcc, s48, v2
	s_cmp_eq_u64 vcc, exec
	s_cbranch_scc0 .Lmy_A_rare1
	v_mov_b32_e32 v223, 1.0

; __device__ __forceinline__ void pv_d0(f32x16* o, int vb, bf16x8 pa0, bf16x8 pa1, bf16x8 pa2, bf16x8 pa3) {
;     ...
;   const s16x4 l0 = tr_read<v_rd_off(0, 0, 0)>(vb), h0 = tr_read<v_rd_off(0, 0, 1)>(vb);
;   const s16x4 l1 = tr_read<v_rd_off(0, 1, 0)>(vb), h1 = tr_read<v_rd_off(0, 1, 1)>(vb);
;   const s16x4 l2 = tr_read<v_rd_off(0, 2, 0)>(vb), h2 = tr_read<v_rd_off(0, 2, 1)>(vb);
;   const s16x4 l3 = tr_read<v_rd_off(0, 3, 0)>(vb), h3 = tr_read<v_rd_off(0, 3, 1)>(vb);
;   const s16x4 l4 = tr_read<v_rd_off(1, 0, 0)>(vb), h4 = tr_read<v_rd_off(1, 0, 1)>(vb);
;   asm volatile("s_waitcnt lgkmcnt(8)" ::: "memory"); SBAR();
;   o[0] = __builtin_amdgcn_mfma_f32_32x32x16_bf16(pa0, PK(l0, h0), o[0], 0, 0, 0);
;   const s16x4 l5 = tr_read<v_rd_off(1, 1, 0)>(vb), h5 = tr_read<v_rd_off(1, 1, 1)>(vb);
;   asm volatile("s_waitcnt lgkmcnt(8)" ::: "memory"); SBAR();
;   o[0] = __builtin_amdgcn_mfma_f32_32x32x16_bf16(pa1, PK(l1, h1), o[0], 0, 0, 0);
;   const s16x4 l6 = tr_read<v_rd_off(1, 2, 0)>(vb), h6 = tr_read<v_rd_off(1, 2, 1)>(vb);
;   asm volatile("s_waitcnt lgkmcnt(8)" ::: "memory"); SBAR();
;   o[0] = __builtin_amdgcn_mfma_f32_32x32x16_bf16(pa2, PK(l2, h2), o[0], 0, 0, 0);
;   const s16x4 l7 = tr_read<v_rd_off(1, 3, 0)>(vb), h7 = tr_read<v_rd_off(1, 3, 1)>(vb);
;   asm volatile("s_waitcnt lgkmcnt(8)" ::: "memory"); SBAR();
;   o[0] = __builtin_amdgcn_mfma_f32_32x32x16_bf16(pa3, PK(l3, h3), o[0], 0, 0, 0);
;   const s16x4 l8 = tr_read<v_rd_off(2, 0, 0)>(vb), h8 = tr_read<v_rd_off(2, 0, 1)>(vb);
;   asm volatile("s_waitcnt lgkmcnt(8)" ::: "memory"); SBAR();
;   o[1] = __builtin_amdgcn_mfma_f32_32x32x16_bf16(pa0, PK(l4, h4), o[1], 0, 0, 0);
;   const s16x4 l9 = tr_read<v_rd_off(2, 1, 0)>(vb), h9 = tr_read<v_rd_off(2, 1, 1)>(vb);
;   asm volatile("s_waitcnt lgkmcnt(8)" ::: "memory"); SBAR();
;   o[1] = __builtin_amdgcn_mfma_f32_32x32x16_bf16(pa1, PK(l5, h5), o[1], 0, 0, 0);
;   const s16x4 l10 = tr_read<v_rd_off(2, 2, 0)>(vb), h10 = tr_read<v_rd_off(2, 2, 1)>(vb);
;   asm volatile("s_waitcnt lgkmcnt(8)" ::: "memory"); SBAR();
;   o[1] = __builtin_amdgcn_mfma_f32_32x32x16_bf16(pa2, PK(l6, h6), o[1], 0, 0, 0);
;   const s16x4 l11 = tr_read<v_rd_off(2, 3, 0)>(vb), h11 = tr_read<v_rd_off(2, 3, 1)>(vb);
;   asm volatile("s_waitcnt lgkmcnt(8)" ::: "memory"); SBAR();
;   o[1] = __builtin_amdgcn_mfma_f32_32x32x16_bf16(pa3, PK(l7, h7), o[1], 0, 0, 0);
.LBB0_347:
	s_cmpk_lg_u32 s63, 0xff00
	s_cselect_b64 s[6:7], -1, 0
.LBB0_349:
	ds_read_b64_tr_b16 v[150:151], v222 offset:0
	ds_read_b64_tr_b16 v[152:153], v222 offset:0x800
	ds_read_b64_tr_b16 v[154:155], v222 offset:0x1000
	ds_read_b64_tr_b16 v[156:157], v222 offset:0x1800
	ds_read_b64_tr_b16 v[158:159], v222 offset:0x2000
	ds_read_b64_tr_b16 v[160:161], v222 offset:0x2800
	ds_read_b64_tr_b16 v[162:163], v222 offset:0x3000
	ds_read_b64_tr_b16 v[164:165], v222 offset:0x3800
	ds_read_b64_tr_b16 v[166:167], v222 offset:0x200
	ds_read_b64_tr_b16 v[168:169], v222 offset:0xa00
	s_waitcnt lgkmcnt(8)
	s_nop 0
	v_mfma_f32_32x32x16_bf16 v[112:127], v[2:5], v[150:153], v[112:127]
	ds_read_b64_tr_b16 v[150:151], v222 offset:0x1200
	ds_read_b64_tr_b16 v[152:153], v222 offset:0x1a00
	s_waitcnt lgkmcnt(8)
	v_mfma_f32_32x32x16_bf16 v[112:127], v[6:9], v[154:157], v[112:127]
	ds_read_b64_tr_b16 v[154:155], v222 offset:0x2200
	ds_read_b64_tr_b16 v[156:157], v222 offset:0x2a00
	s_waitcnt lgkmcnt(8)
	v_mfma_f32_32x32x16_bf16 v[112:127], v[10:13], v[158:161], v[112:127]
	ds_read_b64_tr_b16 v[158:159], v222 offset:0x3200
	ds_read_b64_tr_b16 v[160:161], v222 offset:0x3a00
	s_waitcnt lgkmcnt(8)
	v_mfma_f32_32x32x16_bf16 v[112:127], v[144:147], v[162:165], v[112:127]
	ds_read_b64_tr_b16 v[162:163], v222 offset:0x400
	ds_read_b64_tr_b16 v[164:165], v222 offset:0xc00
	s_waitcnt lgkmcnt(8)
	v_mfma_f32_32x32x16_bf16 v[64:79], v[2:5], v[166:169], v[64:79]
	ds_read_b64_tr_b16 v[166:167], v222 offset:0x1400
	ds_read_b64_tr_b16 v[168:169], v222 offset:0x1c00
	s_waitcnt lgkmcnt(8)
	v_mfma_f32_32x32x16_bf16 v[64:79], v[6:9], v[150:153], v[64:79]
	ds_read_b64_tr_b16 v[150:151], v222 offset:0x2400
	ds_read_b64_tr_b16 v[152:153], v222 offset:0x2c00
	s_waitcnt lgkmcnt(8)
	v_mfma_f32_32x32x16_bf16 v[64:79], v[10:13], v[154:157], v[64:79]
	ds_read_b64_tr_b16 v[154:155], v222 offset:0x3400
	ds_read_b64_tr_b16 v[156:157], v222 offset:0x3c00
	s_waitcnt lgkmcnt(8)
	v_mfma_f32_32x32x16_bf16 v[64:79], v[144:147], v[158:161], v[64:79]
	ds_read_b64_tr_b16 v[158:159], v222 offset:0x600
	ds_read_b64_tr_b16 v[160:161], v222 offset:0xe00
	s_waitcnt lgkmcnt(8)
	v_mfma_f32_32x32x16_bf16 v[16:31], v[2:5], v[162:165], v[16:31]
	ds_read_b64_tr_b16 v[162:163], v222 offset:0x1600
	ds_read_b64_tr_b16 v[164:165], v222 offset:0x1e00
	s_waitcnt lgkmcnt(8)
	v_mfma_f32_32x32x16_bf16 v[16:31], v[6:9], v[166:169], v[16:31]
	ds_read_b64_tr_b16 v[166:167], v222 offset:0x2600
	ds_read_b64_tr_b16 v[168:169], v222 offset:0x2e00
	s_waitcnt lgkmcnt(8)
	v_mfma_f32_32x32x16_bf16 v[16:31], v[10:13], v[150:153], v[16:31]
	ds_read_b64_tr_b16 v[150:151], v222 offset:0x3600
	ds_read_b64_tr_b16 v[152:153], v222 offset:0x3e00
	s_waitcnt lgkmcnt(8)
	v_mfma_f32_32x32x16_bf16 v[16:31], v[144:147], v[154:157], v[16:31]
	s_waitcnt lgkmcnt(6)
	v_mfma_f32_32x32x16_bf16 v[32:47], v[2:5], v[158:161], v[32:47]
	s_waitcnt lgkmcnt(4)
	v_mfma_f32_32x32x16_bf16 v[32:47], v[6:9], v[162:165], v[32:47]
	s_waitcnt lgkmcnt(2)
	v_mfma_f32_32x32x16_bf16 v[32:47], v[10:13], v[166:169], v[32:47]
	s_waitcnt lgkmcnt(0)
	v_mfma_f32_32x32x16_bf16 v[32:47], v[144:147], v[150:153], v[32:47]
	s_andn2_b64 vcc, exec, s[6:7]
	s_cbranch_vccnz .LBB0_351
	s_xor_b32 s6, s64, 0x4000
	s_add_i32 s6, s6, 0
	v_add_u32_e32 v2, s6, v209
	s_waitcnt vmcnt(0)
	ds_write_b128 v2, v[176:179]
	v_add_u32_e32 v2, s6, v210
	ds_write_b128 v2, v[180:183]
	v_add_u32_e32 v2, s6, v212
	ds_write_b128 v2, v[184:187] offset:32768
	v_add_u32_e32 v2, s6, v213
	ds_write_b128 v2, v[188:191] offset:32768

; #define SBAR() __builtin_amdgcn_sched_barrier(0)
; #define SLOAD2(k0) do { vs0 = *reinterpret_cast<const bf16x8*>(&Vh[(long)((k0) + sr) * ldv + sc]); vs1 = *reinterpret_cast<const bf16x8*>(&Vh[(long)((k0) + 32 + sr) * ldv + sc]); \
;     ks0 = *reinterpret_cast<const bf16x8*>(&Kh[(long)((k0) + sr) * ldk + sc]); ks1 = *reinterpret_cast<const bf16x8*>(&Kh[(long)((k0) + 32 + sr) * ldk + sc]); } while (0)
; #define RESC2(O, SL, a) do { if (__any((a) < 1.f)) { if (hi == 0) SL[r32] = (a); asm volatile("s_waitcnt lgkmcnt(0)" ::: "memory"); \
;     _Pragma("unroll") for (int d = 0; d < 4; ++d) _Pragma("unroll") for (int r = 0; r < 16; ++r) O[d][r] *= SL[crow(r, hi)]; } } while (0)
; __device__ __forceinline__ void attn_unit_A2(const bf16_t* __restrict__ Qb, int ldq, const bf16_t* __restrict__ Kh, int ldk, const bf16_t* __restrict__ Vh, int ldv, int nkeys, int q0, ...
;     ...
;     qkt_map_roll<1>(s0, s1, kbA + b * SHM_K, qaA);
;     SBAR();
;     if (nearb) {
; #pragma unroll
;       for (int r = 0; r < 8; ++r) { s0[r] += tb_[(r & 3) + 8 * (r >> 2)]; s1[r] += tb_[32 + (r & 3) + 8 * (r >> 2)]; }
;       SBAR();
; #pragma unroll
;       for (int r = 8; r < 16; ++r) { s0[r] += tb_[(r & 3) + 8 * (r >> 2)]; s1[r] += tb_[32 + (r & 3) + 8 * (r >> 2)]; } }
;     SBAR();
;     softmax_tile(s0, s1, m1, l1, al1, cb, pa0, pa1, pa2, pa3);
;     RESC2(ob, sl1, al1);
;     SBAR();
;     if (j + 1 < NT) SLOAD2(kt0 + KVBLK);
.Lmy_A_noload2:
	s_nop 8
	s_branch .Lmy_A_sm1x

.LBB0_486:
	s_add_i32 s46, s44, s45
	s_cmp_gt_i32 s45, s11
	s_cselect_b64 s[6:7], -1, 0
	s_cmpk_lt_i32 s46, 0xfbc2
	s_cselect_b64 s[8:9], -1, 0
	v_sub_f32_e32 v82, 0, v222
	s_or_b64 s[8:9], s[6:7], s[8:9]
	v_cndmask_b32_e64 v243, -v222, v82, s[8:9]
	v_cmp_neq_f32_e32 vcc, v243, v241
	s_cmp_eq_u64 vcc, 0
	s_cselect_b64 s[6:7], -1, 0
	s_cbranch_scc1 .Lmy_negm_skipD0
	v_cndmask_b32_e64 v81, v243, v81, s[6:7]
	v_cndmask_b32_e64 v80, v243, v80, s[6:7]
	v_cndmask_b32_e64 v79, v243, v79, s[6:7]
	v_cndmask_b32_e64 v78, v243, v78, s[6:7]
	v_cndmask_b32_e64 v77, v243, v77, s[6:7]
	v_cndmask_b32_e64 v76, v243, v76, s[6:7]
	v_cndmask_b32_e64 v75, v243, v75, s[6:7]
	v_cndmask_b32_e64 v74, v243, v74, s[6:7]
	v_cndmask_b32_e64 v73, v243, v73, s[6:7]
	v_cndmask_b32_e64 v72, v243, v72, s[6:7]
	v_cndmask_b32_e64 v71, v243, v71, s[6:7]
	v_cndmask_b32_e64 v70, v243, v70, s[6:7]
	v_cndmask_b32_e64 v69, v243, v69, s[6:7]
	v_cndmask_b32_e64 v68, v243, v68, s[6:7]
	v_cndmask_b32_e64 v67, v243, v67, s[6:7]
	v_cndmask_b32_e64 v66, v243, v66, s[6:7]
; #define SBAR() __builtin_amdgcn_sched_barrier(0)
; __device__ __forceinline__ void qkt8_fsm(f32x16& p0, f32x16& p1, const f32x16& negm, int kb, const bf16x8* qr, f32x16& q0p, f32x16& q1p, float alpha, float& l_reg, bf16x8& pa0, bf16x8& pa1, bf16x8& pa2, bf16x8& pa3) {
;   float sm[4];
;   const int a0 = kb ^ (0 << 5); const bf16x8 x0 = lds_rd128<0>(a0), y0 = lds_rd128<8192>(a0);
;   const int a1 = kb ^ (1 << 5); const bf16x8 x1 = lds_rd128<0>(a1), y1 = lds_rd128<8192>(a1);
;   const int a2 = kb ^ (2 << 5); const bf16x8 x2 = lds_rd128<0>(a2), y2 = lds_rd128<8192>(a2);
;   asm volatile("s_waitcnt lgkmcnt(4)" ::: "memory"); SBAR();
;   p0 = __builtin_amdgcn_mfma_f32_32x32x16_bf16(x0, qr[0], negm, 0, 0, 0); p1 = __builtin_amdgcn_mfma_f32_32x32x16_bf16(y0, qr[0], negm, 0, 0, 0);
;   fsm_slice<0>(q0p, q1p, alpha, l_reg, pa0, pa1, pa2, pa3, sm); SBAR();
;   const int a3 = kb ^ (3 << 5); const bf16x8 x3 = lds_rd128<0>(a3), y3 = lds_rd128<8192>(a3);
;   asm volatile("s_waitcnt lgkmcnt(4)" ::: "memory"); SBAR();
;   p0 = __builtin_amdgcn_mfma_f32_32x32x16_bf16(x1, qr[1], p0, 0, 0, 0); p1 = __builtin_amdgcn_mfma_f32_32x32x16_bf16(y1, qr[1], p1, 0, 0, 0);
;   fsm_slice<1>(q0p, q1p, alpha, l_reg, pa0, pa1, pa2, pa3, sm); SBAR();
;   const int a4 = kb ^ (4 << 5); const bf16x8 x4 = lds_rd128<0>(a4), y4 = lds_rd128<8192>(a4);
;   asm volatile("s_waitcnt lgkmcnt(4)" ::: "memory"); SBAR();
;   p0 = __builtin_amdgcn_mfma_f32_32x32x16_bf16(x2, qr[2], p0, 0, 0, 0); p1 = __builtin_amdgcn_mfma_f32_32x32x16_bf16(y2, qr[2], p1, 0, 0, 0);
;   fsm_slice<2>(q0p, q1p, alpha, l_reg, pa0, pa1, pa2, pa3, sm); SBAR();
;   const int a5 = kb ^ (5 << 5); const bf16x8 x5 = lds_rd128<0>(a5), y5 = lds_rd128<8192>(a5);
;   asm volatile("s_waitcnt lgkmcnt(4)" ::: "memory"); SBAR();
;   p0 = __builtin_amdgcn_mfma_f32_32x32x16_bf16(x3, qr[3], p0, 0, 0, 0); p1 = __builtin_amdgcn_mfma_f32_32x32x16_bf16(y3, qr[3], p1, 0, 0, 0);
;   fsm_slice<3>(q0p, q1p, alpha, l_reg, pa0, pa1, pa2, pa3, sm); SBAR();
;   const int a6 = kb ^ (6 << 5); const bf16x8 x6 = lds_rd128<0>(a6), y6 = lds_rd128<8192>(a6);
;   asm volatile("s_waitcnt lgkmcnt(4)" ::: "memory"); SBAR();
;   p0 = __builtin_amdgcn_mfma_f32_32x32x16_bf16(x4, qr[4], p0, 0, 0, 0); p1 = __builtin_amdgcn_mfma_f32_32x32x16_bf16(y4, qr[4], p1, 0, 0, 0);
;   fsm_slice<4>(q0p, q1p, alpha, l_reg, pa0, pa1, pa2, pa3, sm); SBAR();
.Lmy_negm_skipD0:
	ds_read_b128 v[82:85], v233 offset:0
	ds_read_b128 v[178:181], v233 offset:0x2000
	ds_read_b128 v[182:185], v232 offset:0
	ds_read_b128 v[186:189], v232 offset:0x2000
	ds_read_b128 v[192:195], v231 offset:0
	ds_read_b128 v[244:247], v231 offset:0x2000
	s_waitcnt lgkmcnt(4)
	s_nop 1
	v_mfma_f32_32x32x16_bf16 v[98:113], v[82:85], v[142:145], v[66:81]
	v_mfma_f32_32x32x16_bf16 v[82:97], v[178:181], v[142:145], v[66:81]
	ds_read_b128 v[178:181], v230 offset:0
	ds_read_b128 v[248:251], v230 offset:0x2000
	s_waitcnt lgkmcnt(4)
	v_mfma_f32_32x32x16_bf16 v[98:113], v[182:185], v[138:141], v[98:113]
	v_mfma_f32_32x32x16_bf16 v[82:97], v[186:189], v[138:141], v[82:97]
	ds_read_b128 v[182:185], v229 offset:0
	ds_read_b128 v[186:189], v229 offset:0x2000
	s_waitcnt lgkmcnt(4)
	v_mfma_f32_32x32x16_bf16 v[98:113], v[192:195], v[134:137], v[98:113]
	v_add_f32_e32 v192, v146, v148
	v_add_f32_e32 v193, v177, v175
	v_add_f32_e32 v194, v147, v149
	v_add_f32_e32 v195, v176, v174
	v_add_f32_e32 v192, v150, v192
	v_add_f32_e32 v193, v173, v193
	v_add_f32_e32 v194, v151, v194
	v_mfma_f32_32x32x16_bf16 v[82:97], v[244:247], v[134:137], v[82:97]
	v_add_f32_e32 v195, v172, v195
	v_add_f32_e32 v202, v152, v192
	v_add_f32_e32 v203, v171, v193
	v_add_f32_e32 v204, v153, v194
	v_add_f32_e32 v205, v170, v195
	ds_read_b128 v[192:195], v228 offset:0
	ds_read_b128 v[244:247], v228 offset:0x2000
	s_waitcnt lgkmcnt(4)
	v_mfma_f32_32x32x16_bf16 v[98:113], v[178:181], v[130:133], v[98:113]
	v_add_f32_e32 v178, v154, v202
	v_add_f32_e32 v179, v169, v203
	v_add_f32_e32 v180, v155, v204
	v_add_f32_e32 v181, v168, v205
	v_add_f32_e32 v178, v156, v178
	v_add_f32_e32 v179, v167, v179
	v_add_f32_e32 v180, v157, v180
	v_mfma_f32_32x32x16_bf16 v[82:97], v[248:251], v[130:133], v[82:97]
	v_add_f32_e32 v181, v166, v181
	v_add_f32_e32 v178, v158, v178
	v_add_f32_e32 v179, v165, v179
	v_add_f32_e32 v180, v159, v180
	v_add_f32_e32 v181, v164, v181
	v_add_f32_e32 v202, v160, v178
	v_add_f32_e32 v203, v163, v179
	v_add_f32_e32 v204, v161, v180
	v_add_f32_e32 v205, v162, v181
	ds_read_b128 v[178:181], v227 offset:0
	ds_read_b128 v[248:251], v227 offset:0x2000
	s_waitcnt lgkmcnt(4)
	v_mfma_f32_32x32x16_bf16 v[98:113], v[182:185], v[126:129], v[98:113]
	v_add_f32_e32 v182, v202, v203
	v_add_f32_e32 v183, v204, v205
	v_add_f32_e32 v239, v182, v183
	v_mov_b32_e32 v240, v239
	v_cvt_pk_bf16_f32 v146, v146, v177
	v_cvt_pk_bf16_f32 v147, v147, v176
	v_cvt_pk_bf16_f32 v148, v148, v175
	v_mfma_f32_32x32x16_bf16 v[82:97], v[186:189], v[126:129], v[82:97]
	v_cvt_pk_bf16_f32 v149, v149, v174
	s_nop 0
	v_permlane32_swap_b32_e32 v239, v240
	ds_read_b128 v[174:177], v226 offset:0
	ds_read_b128 v[182:185], v226 offset:0x2000
	s_waitcnt lgkmcnt(4)
	v_mfma_f32_32x32x16_bf16 v[98:113], v[192:195], v[122:125], v[98:113]
	v_cvt_pk_bf16_f32 v150, v150, v173
	v_cvt_pk_bf16_f32 v151, v151, v172
	v_cvt_pk_bf16_f32 v152, v152, v171
	v_cvt_pk_bf16_f32 v153, v153, v170
	s_nop 0
	v_mfma_f32_32x32x16_bf16 v[82:97], v[244:247], v[122:125], v[82:97]
	s_waitcnt lgkmcnt(2)
	v_mfma_f32_32x32x16_bf16 v[98:113], v[178:181], v[118:121], v[98:113]
	v_cvt_pk_bf16_f32 v154, v154, v169
	v_cvt_pk_bf16_f32 v155, v155, v168
	v_cvt_pk_bf16_f32 v156, v156, v167
	v_cvt_pk_bf16_f32 v157, v157, v166
	s_nop 0
	v_mfma_f32_32x32x16_bf16 v[82:97], v[248:251], v[118:121], v[82:97]
	s_waitcnt lgkmcnt(0)
	v_mfma_f32_32x32x16_bf16 v[98:113], v[174:177], v[114:117], v[98:113]
	v_cvt_pk_bf16_f32 v158, v158, v165
	v_cvt_pk_bf16_f32 v159, v159, v164
	v_cvt_pk_bf16_f32 v160, v160, v163
	v_cvt_pk_bf16_f32 v161, v161, v162
	s_nop 0
	v_mfma_f32_32x32x16_bf16 v[82:97], v[182:185], v[114:117], v[82:97]
	v_add_u32_e32 v238, s45, v212
	v_add_u32_e32 v170, 64, v238
	v_add_u32_e32 v172, 0x60, v238
	v_mad_i64_i32 v[162:163], s[50:51], v170, s55, v[198:199]
	v_mad_i64_i32 v[166:167], s[50:51], v172, s55, v[198:199]
	v_mad_i64_i32 v[170:171], s[50:51], v170, s55, v[200:201]
	v_mad_i64_i32 v[174:175], s[50:51], v172, s55, v[200:201]
	global_load_dwordx4 v[162:165], v[162:163], off
	s_nop 0
	global_load_dwordx4 v[166:169], v[166:167], off
	s_nop 0
	global_load_dwordx4 v[170:173], v[170:171], off
	s_nop 0
	global_load_dwordx4 v[174:177], v[174:175], off
	s_and_b64 vcc, exec, s[8:9]
	s_cbranch_vccnz .LBB0_488
	ds_read2_b32 v[178:179], v236 offset1:1
	ds_read2_b32 v[180:181], v236 offset0:2 offset1:3
	ds_read2_b32 v[182:183], v236 offset0:8 offset1:9
	ds_read2_b32 v[184:185], v236 offset0:10 offset1:11
	ds_read2_b32 v[186:187], v236 offset0:16 offset1:17
	ds_read2_b32 v[188:189], v236 offset0:18 offset1:19
	ds_read2_b32 v[192:193], v236 offset0:24 offset1:25
	ds_read2_b32 v[194:195], v236 offset0:26 offset1:27
	ds_read2_b32 v[202:203], v236 offset0:32 offset1:33
	ds_read2_b32 v[204:205], v236 offset0:34 offset1:35
	ds_read2_b32 v[244:245], v236 offset0:40 offset1:41
	ds_read2_b32 v[246:247], v236 offset0:42 offset1:43
	s_waitcnt lgkmcnt(11)
	v_add_f32_e32 v98, v98, v178
	v_add_f32_e32 v99, v99, v179
	s_waitcnt lgkmcnt(5)
	v_add_f32_e32 v110, v110, v192
	v_add_f32_e32 v111, v111, v193
	v_add_f32_e32 v108, v108, v188
	v_add_f32_e32 v109, v109, v189
	v_add_f32_e32 v106, v106, v186
	v_add_f32_e32 v107, v107, v187
	ds_read2_b32 v[178:179], v236 offset0:48 offset1:49
	ds_read2_b32 v[186:187], v236 offset0:50 offset1:51
	ds_read2_b32 v[188:189], v236 offset0:56 offset1:57
	ds_read2_b32 v[192:193], v236 offset0:58 offset1:59
	s_waitcnt lgkmcnt(8)
	v_add_f32_e32 v112, v112, v194
	v_add_f32_e32 v113, v113, v195
	v_add_f32_e32 v104, v104, v184
	v_add_f32_e32 v105, v105, v185
	v_add_f32_e32 v102, v102, v182
	v_add_f32_e32 v103, v103, v183
	v_add_f32_e32 v100, v100, v180
	v_add_f32_e32 v101, v101, v181
	s_waitcnt lgkmcnt(7)
	v_add_f32_e32 v82, v82, v202
	v_add_f32_e32 v83, v83, v203
	s_waitcnt lgkmcnt(0)
	v_add_f32_e32 v96, v96, v192
	v_add_f32_e32 v97, v97, v193
	v_add_f32_e32 v94, v94, v188
	v_add_f32_e32 v95, v95, v189
	v_add_f32_e32 v92, v92, v186
	v_add_f32_e32 v93, v93, v187
	v_add_f32_e32 v90, v90, v178
	v_add_f32_e32 v91, v91, v179
	v_add_f32_e32 v88, v88, v246
	v_add_f32_e32 v89, v89, v247
	v_add_f32_e32 v86, v86, v244
	v_add_f32_e32 v87, v87, v245
	v_add_f32_e32 v84, v84, v204
	v_add_f32_e32 v85, v85, v205

; template <int K>
; __device__ __forceinline__ void psm_slice(f32x16& p0, f32x16& p1, float& mC, float& alpha, float (&mx)[4]) {
;   if constexpr (K == 0) { mx[0] = p0[0]; mx[1] = p0[1]; mx[2] = p0[2]; mx[3] = p0[3]; }
;   else if constexpr (K >= 1 && K <= 3) {
; #pragma unroll
;     for (int r = 4 * K; r < 4 * K + 4; ++r) mx[r & 3] = fmaxf(mx[r & 3], p0[r]);
;   } else if constexpr (K >= 4 && K <= 7) {
; #pragma unroll
;     for (int r = 4 * (K - 4); r < 4 * (K - 4) + 4; ++r) mx[r & 3] = fmaxf(mx[r & 3], p1[r]);
;   } else if constexpr (K == 8) {
;     float pmax = fmaxf(fmaxf(mx[0], mx[1]), fmaxf(mx[2], mx[3]));
;     { auto rr = __builtin_amdgcn_permlane32_swap(__float_as_uint(pmax), __float_as_uint(pmax), false, false);
;       pmax = fmaxf(__uint_as_float(rr[0]), __uint_as_float(rr[1])); }
;     if (__builtin_expect(__all(pmax <= THR2), 1)) { alpha = 1.f; }
;     else { const float delta = fmaxf(pmax, 0.f); alpha = __builtin_amdgcn_exp2f(-delta); mC += delta;
; #pragma unroll
;       for (int r = 0; r < 16; ++r) p0[r] -= delta;
; #pragma unroll
;       for (int r = 0; r < 16; ++r) p1[r] -= delta; }
;   } else if constexpr (K >= 9 && K <= 12) {
; #pragma unroll
;     for (int r = 4 * (K - 9); r < 4 * (K - 9) + 4; ++r) p0[r] = __builtin_amdgcn_exp2f(p0[r]);
;   } else if constexpr (K >= 13 && K <= 15) {
; #pragma unroll
;     for (int r = (K == 13 ? 0 : K == 14 ? 6 : 11); r < (K == 13 ? 6 : K == 14 ? 11 : 16); ++r) p1[r] = __builtin_amdgcn_exp2f(p1[r]);
;   }
; }
.LBB0_493:
	v_cndmask_b32_e64 v241, v243, v241, s[6:7]
	s_add_i32 s6, s45, 64
	s_add_i32 s46, s46, 64
	s_cmp_gt_i32 s6, s11
	s_cselect_b64 s[6:7], -1, 0
	s_cmpk_lt_i32 s46, 0xfbc2
	s_cselect_b64 s[8:9], -1, 0
	v_exp_f32_e32 v154, v82
	v_sub_f32_e32 v82, 0, v222
	s_or_b64 s[8:9], s[6:7], s[8:9]
	v_cndmask_b32_e64 v243, -v222, v82, s[8:9]
	v_exp_f32_e32 v146, v98
	v_exp_f32_e32 v177, v99
	v_exp_f32_e32 v147, v100
	v_exp_f32_e32 v176, v101
	v_exp_f32_e32 v148, v102
	v_exp_f32_e32 v175, v103
	v_exp_f32_e32 v149, v104
	v_exp_f32_e32 v174, v105
	v_exp_f32_e32 v150, v106
	v_exp_f32_e32 v173, v107
	v_exp_f32_e32 v151, v108
	v_exp_f32_e32 v172, v109
	v_exp_f32_e32 v152, v110
	v_exp_f32_e32 v171, v111
	v_exp_f32_e32 v153, v112
	v_exp_f32_e32 v170, v113
	v_exp_f32_e32 v169, v83
	v_exp_f32_e32 v155, v84
	v_exp_f32_e32 v168, v85
	v_exp_f32_e32 v156, v86
	v_exp_f32_e32 v167, v87
	v_exp_f32_e32 v157, v88
	v_exp_f32_e32 v166, v89
	v_exp_f32_e32 v158, v90
	v_exp_f32_e32 v165, v91
	v_exp_f32_e32 v159, v92
	v_exp_f32_e32 v164, v93
	v_exp_f32_e32 v160, v94
	v_exp_f32_e32 v163, v95
	v_exp_f32_e32 v161, v96
	v_exp_f32_e32 v162, v97
	v_cmp_neq_f32_e32 vcc, v243, v241
	s_cmp_eq_u64 vcc, 0
	s_cselect_b64 s[6:7], -1, 0
	s_cbranch_scc1 .Lmy_negm_skipD1
	v_cndmask_b32_e64 v81, v243, v81, s[6:7]
	v_cndmask_b32_e64 v80, v243, v80, s[6:7]
	v_cndmask_b32_e64 v79, v243, v79, s[6:7]
	v_cndmask_b32_e64 v78, v243, v78, s[6:7]
	v_cndmask_b32_e64 v77, v243, v77, s[6:7]
	v_cndmask_b32_e64 v76, v243, v76, s[6:7]
	v_cndmask_b32_e64 v75, v243, v75, s[6:7]
	v_cndmask_b32_e64 v74, v243, v74, s[6:7]
	v_cndmask_b32_e64 v73, v243, v73, s[6:7]
	v_cndmask_b32_e64 v72, v243, v72, s[6:7]
	v_cndmask_b32_e64 v71, v243, v71, s[6:7]
	v_cndmask_b32_e64 v70, v243, v70, s[6:7]
	v_cndmask_b32_e64 v69, v243, v69, s[6:7]
	v_cndmask_b32_e64 v68, v243, v68, s[6:7]
	v_cndmask_b32_e64 v67, v243, v67, s[6:7]
	v_cndmask_b32_e64 v66, v243, v66, s[6:7]
; #define SBAR() __builtin_amdgcn_sched_barrier(0)
; __device__ __forceinline__ void qkt8_fsm(f32x16& p0, f32x16& p1, const f32x16& negm, int kb, const bf16x8* qr, f32x16& q0p, f32x16& q1p, float alpha, float& l_reg, bf16x8& pa0, bf16x8& pa1, bf16x8& pa2, bf16x8& pa3) {
;   float sm[4];
;   const int a0 = kb ^ (0 << 5); const bf16x8 x0 = lds_rd128<0>(a0), y0 = lds_rd128<8192>(a0);
;   const int a1 = kb ^ (1 << 5); const bf16x8 x1 = lds_rd128<0>(a1), y1 = lds_rd128<8192>(a1);
;   const int a2 = kb ^ (2 << 5); const bf16x8 x2 = lds_rd128<0>(a2), y2 = lds_rd128<8192>(a2);
;   asm volatile("s_waitcnt lgkmcnt(4)" ::: "memory"); SBAR();
;   p0 = __builtin_amdgcn_mfma_f32_32x32x16_bf16(x0, qr[0], negm, 0, 0, 0); p1 = __builtin_amdgcn_mfma_f32_32x32x16_bf16(y0, qr[0], negm, 0, 0, 0);
;   fsm_slice<0>(q0p, q1p, alpha, l_reg, pa0, pa1, pa2, pa3, sm); SBAR();
;   const int a3 = kb ^ (3 << 5); const bf16x8 x3 = lds_rd128<0>(a3), y3 = lds_rd128<8192>(a3);
;   asm volatile("s_waitcnt lgkmcnt(4)" ::: "memory"); SBAR();
;   p0 = __builtin_amdgcn_mfma_f32_32x32x16_bf16(x1, qr[1], p0, 0, 0, 0); p1 = __builtin_amdgcn_mfma_f32_32x32x16_bf16(y1, qr[1], p1, 0, 0, 0);
;   fsm_slice<1>(q0p, q1p, alpha, l_reg, pa0, pa1, pa2, pa3, sm); SBAR();
;   const int a4 = kb ^ (4 << 5); const bf16x8 x4 = lds_rd128<0>(a4), y4 = lds_rd128<8192>(a4);
;   asm volatile("s_waitcnt lgkmcnt(4)" ::: "memory"); SBAR();
;   p0 = __builtin_amdgcn_mfma_f32_32x32x16_bf16(x2, qr[2], p0, 0, 0, 0); p1 = __builtin_amdgcn_mfma_f32_32x32x16_bf16(y2, qr[2], p1, 0, 0, 0);
;   fsm_slice<2>(q0p, q1p, alpha, l_reg, pa0, pa1, pa2, pa3, sm); SBAR();
;   const int a5 = kb ^ (5 << 5); const bf16x8 x5 = lds_rd128<0>(a5), y5 = lds_rd128<8192>(a5);
;   asm volatile("s_waitcnt lgkmcnt(4)" ::: "memory"); SBAR();
;   p0 = __builtin_amdgcn_mfma_f32_32x32x16_bf16(x3, qr[3], p0, 0, 0, 0); p1 = __builtin_amdgcn_mfma_f32_32x32x16_bf16(y3, qr[3], p1, 0, 0, 0);
;   fsm_slice<3>(q0p, q1p, alpha, l_reg, pa0, pa1, pa2, pa3, sm); SBAR();
;   const int a6 = kb ^ (6 << 5); const bf16x8 x6 = lds_rd128<0>(a6), y6 = lds_rd128<8192>(a6);
;   asm volatile("s_waitcnt lgkmcnt(4)" ::: "memory"); SBAR();
;   p0 = __builtin_amdgcn_mfma_f32_32x32x16_bf16(x4, qr[4], p0, 0, 0, 0); p1 = __builtin_amdgcn_mfma_f32_32x32x16_bf16(y4, qr[4], p1, 0, 0, 0);
;   fsm_slice<4>(q0p, q1p, alpha, l_reg, pa0, pa1, pa2, pa3, sm); SBAR();
.Lmy_negm_skipD1:
	s_waitcnt lgkmcnt(0)
	s_barrier
	ds_read_b128 v[82:85], v213 offset:0
	ds_read_b128 v[178:181], v213 offset:0x2000
	ds_read_b128 v[182:185], v218 offset:0
	ds_read_b128 v[186:189], v218 offset:0x2000
	ds_read_b128 v[192:195], v219 offset:0
	ds_read_b128 v[244:247], v219 offset:0x2000
	s_waitcnt lgkmcnt(4)
	s_nop 0
	v_mfma_f32_32x32x16_bf16 v[98:113], v[82:85], v[142:145], v[66:81]
	v_mfma_f32_32x32x16_bf16 v[82:97], v[178:181], v[142:145], v[66:81]
	ds_read_b128 v[178:181], v220 offset:0
	ds_read_b128 v[248:251], v220 offset:0x2000
	s_waitcnt lgkmcnt(4)
	v_mfma_f32_32x32x16_bf16 v[98:113], v[182:185], v[138:141], v[98:113]
	v_mfma_f32_32x32x16_bf16 v[82:97], v[186:189], v[138:141], v[82:97]
	ds_read_b128 v[182:185], v221 offset:0
	ds_read_b128 v[186:189], v221 offset:0x2000
	s_waitcnt lgkmcnt(4)
	v_mfma_f32_32x32x16_bf16 v[98:113], v[192:195], v[134:137], v[98:113]
	v_add_f32_e32 v192, v148, v146
	v_add_f32_e32 v193, v175, v177
	v_add_f32_e32 v194, v149, v147
	v_add_f32_e32 v195, v174, v176
	v_add_f32_e32 v192, v150, v192
	v_add_f32_e32 v193, v173, v193
	v_add_f32_e32 v194, v151, v194
	v_mfma_f32_32x32x16_bf16 v[82:97], v[244:247], v[134:137], v[82:97]
	v_add_f32_e32 v195, v172, v195
	v_add_f32_e32 v244, v152, v192
	v_add_f32_e32 v245, v171, v193
	v_add_f32_e32 v246, v153, v194
	v_add_f32_e32 v247, v170, v195
	ds_read_b128 v[192:195], v223 offset:0
	ds_read_b128 v[202:205], v223 offset:0x2000
	s_waitcnt lgkmcnt(4)
	v_mfma_f32_32x32x16_bf16 v[98:113], v[178:181], v[130:133], v[98:113]
	v_add_f32_e32 v178, v154, v244
	v_add_f32_e32 v179, v169, v245
	v_add_f32_e32 v180, v155, v246
	v_add_f32_e32 v181, v168, v247
	v_add_f32_e32 v178, v156, v178
	v_add_f32_e32 v179, v167, v179
	v_add_f32_e32 v180, v157, v180
	v_mfma_f32_32x32x16_bf16 v[82:97], v[248:251], v[130:133], v[82:97]
	v_add_f32_e32 v181, v166, v181
	v_add_f32_e32 v178, v158, v178
	v_add_f32_e32 v179, v165, v179
	v_add_f32_e32 v180, v159, v180
	v_add_f32_e32 v181, v164, v181
	v_add_f32_e32 v244, v160, v178
	v_add_f32_e32 v245, v163, v179
	v_add_f32_e32 v250, v161, v180
	v_add_f32_e32 v251, v162, v181
	ds_read_b128 v[178:181], v224 offset:0
	ds_read_b128 v[246:249], v224 offset:0x2000
	s_waitcnt lgkmcnt(4)
	v_mfma_f32_32x32x16_bf16 v[98:113], v[182:185], v[126:129], v[98:113]
	v_add_f32_e32 v182, v245, v244
	v_add_f32_e32 v183, v251, v250
	v_add_f32_e32 v244, v183, v182
	v_mov_b32_e32 v245, v244
	v_cvt_pk_bf16_f32 v146, v146, v177
	v_cvt_pk_bf16_f32 v147, v147, v176
	v_cvt_pk_bf16_f32 v148, v148, v175
	v_mfma_f32_32x32x16_bf16 v[82:97], v[186:189], v[126:129], v[82:97]
	v_cvt_pk_bf16_f32 v149, v149, v174
	s_nop 0
	v_permlane32_swap_b32_e32 v244, v245
	ds_read_b128 v[174:177], v225 offset:0
	ds_read_b128 v[182:185], v225 offset:0x2000
	s_waitcnt lgkmcnt(4)
	v_mfma_f32_32x32x16_bf16 v[98:113], v[192:195], v[122:125], v[98:113]
	v_cvt_pk_bf16_f32 v150, v150, v173
	v_cvt_pk_bf16_f32 v151, v151, v172
	v_cvt_pk_bf16_f32 v152, v152, v171
	v_cvt_pk_bf16_f32 v153, v153, v170
	s_nop 0
	v_mfma_f32_32x32x16_bf16 v[82:97], v[202:205], v[122:125], v[82:97]
	s_waitcnt lgkmcnt(2)
	v_mfma_f32_32x32x16_bf16 v[98:113], v[178:181], v[118:121], v[98:113]
	v_cvt_pk_bf16_f32 v154, v154, v169
	v_cvt_pk_bf16_f32 v155, v155, v168
	v_cvt_pk_bf16_f32 v156, v156, v167
	v_cvt_pk_bf16_f32 v157, v157, v166
	s_nop 0
	v_mfma_f32_32x32x16_bf16 v[82:97], v[246:249], v[118:121], v[82:97]
	s_waitcnt lgkmcnt(0)
	v_mfma_f32_32x32x16_bf16 v[98:113], v[174:177], v[114:117], v[98:113]
	v_cvt_pk_bf16_f32 v158, v158, v165
	v_cvt_pk_bf16_f32 v159, v159, v164
	v_cvt_pk_bf16_f32 v160, v160, v163
	v_cvt_pk_bf16_f32 v161, v161, v162
	s_nop 0
	v_mfma_f32_32x32x16_bf16 v[82:97], v[182:185], v[114:117], v[82:97]
	v_add_u32_e32 v170, 0x80, v238
	v_add_u32_e32 v172, 0xa0, v238
	v_mad_i64_i32 v[162:163], s[46:47], v170, s55, v[198:199]
	v_mad_i64_i32 v[166:167], s[46:47], v172, s55, v[198:199]
	v_mad_i64_i32 v[170:171], s[46:47], v170, s55, v[200:201]
	v_mad_i64_i32 v[174:175], s[46:47], v172, s55, v[200:201]
	global_load_dwordx4 v[162:165], v[162:163], off
	s_nop 0
	global_load_dwordx4 v[166:169], v[166:167], off
	s_nop 0
	global_load_dwordx4 v[170:173], v[170:171], off
	s_nop 0
	global_load_dwordx4 v[174:177], v[174:175], off
	s_and_b64 vcc, exec, s[8:9]
	s_cbranch_vccnz .LBB0_495
	ds_read2_b32 v[178:179], v236 offset0:64 offset1:65
	ds_read2_b32 v[180:181], v236 offset0:66 offset1:67
	ds_read2_b32 v[182:183], v236 offset0:72 offset1:73
	ds_read2_b32 v[184:185], v236 offset0:74 offset1:75
	ds_read2_b32 v[186:187], v236 offset0:80 offset1:81
	ds_read2_b32 v[188:189], v236 offset0:82 offset1:83
	ds_read2_b32 v[192:193], v236 offset0:88 offset1:89
	ds_read2_b32 v[194:195], v236 offset0:90 offset1:91
	ds_read2_b32 v[202:203], v236 offset0:96 offset1:97
	ds_read2_b32 v[204:205], v236 offset0:98 offset1:99
	ds_read2_b32 v[246:247], v236 offset0:104 offset1:105
	ds_read2_b32 v[248:249], v236 offset0:106 offset1:107
	s_waitcnt lgkmcnt(11)
	v_add_f32_e32 v98, v98, v178
	v_add_f32_e32 v99, v99, v179
	s_waitcnt lgkmcnt(5)
	v_add_f32_e32 v110, v110, v192
	v_add_f32_e32 v111, v111, v193
	v_add_f32_e32 v108, v108, v188
	v_add_f32_e32 v109, v109, v189
	v_add_f32_e32 v106, v106, v186
	v_add_f32_e32 v107, v107, v187
	ds_read2_b32 v[178:179], v236 offset0:112 offset1:113
	ds_read2_b32 v[186:187], v236 offset0:114 offset1:115
	ds_read2_b32 v[188:189], v236 offset0:120 offset1:121
	ds_read2_b32 v[192:193], v236 offset0:122 offset1:123
	s_waitcnt lgkmcnt(8)
	v_add_f32_e32 v112, v112, v194
	v_add_f32_e32 v113, v113, v195
	v_add_f32_e32 v104, v104, v184
	v_add_f32_e32 v105, v105, v185
	v_add_f32_e32 v102, v102, v182
	v_add_f32_e32 v103, v103, v183
	v_add_f32_e32 v100, v100, v180
	v_add_f32_e32 v101, v101, v181
	s_waitcnt lgkmcnt(7)
	v_add_f32_e32 v82, v82, v202
	v_add_f32_e32 v83, v83, v203
	s_waitcnt lgkmcnt(0)
	v_add_f32_e32 v96, v96, v192
	v_add_f32_e32 v97, v97, v193
	v_add_f32_e32 v94, v94, v188
	v_add_f32_e32 v95, v95, v189
	v_add_f32_e32 v92, v92, v186
	v_add_f32_e32 v93, v93, v187
	v_add_f32_e32 v90, v90, v178
	v_add_f32_e32 v91, v91, v179
	v_add_f32_e32 v88, v88, v248
	v_add_f32_e32 v89, v89, v249
	v_add_f32_e32 v86, v86, v246
	v_add_f32_e32 v87, v87, v247
	v_add_f32_e32 v84, v84, v204
	v_add_f32_e32 v85, v85, v205
